# previous + the same static priority scheme in GEMM group 1 (in-proj, q-up, kv-up) main loop
# baseline (speedup 1.0000x reference)
.LBB0_198:
	s_and_b64 vcc, exec, s[0:1]
	s_cbranch_vccz .LBB0_316
	s_lshl_b32 s14, s6, 8
	s_lshl_b64 s[24:25], s[14:15], 1
	s_ashr_i32 s5, s3, 31
	v_lshlrev_b32_e32 v2, 5, v2
	s_mul_i32 s5, s24, s5
	s_mul_hi_u32 s7, s24, s3
	v_mul_lo_u32 v16, v9, s6
	s_lshl_b32 s48, s10, 9
	v_and_b32_e32 v17, 32, v2
	v_mul_i32_i24_e32 v2, 64, v5
	v_mul_lo_u32 v19, v4, s6
	s_add_i32 s5, s7, s5
	s_bfe_u32 s6, s6, 0x10017
	s_ashr_i32 s7, s46, 31
	v_lshlrev_b32_e32 v7, 5, v7
	s_ashr_i32 s1, s4, 6
	v_sub_u32_e32 v2, v3, v2
	s_mul_i32 s6, s6, s3
	s_mul_i32 s7, s48, s7
	s_mul_hi_u32 s8, s48, s46
	v_and_b32_e32 v14, 32, v7
	v_lshlrev_b32_e32 v7, 6, v10
	s_ashr_i32 s0, s4, 8
	s_lshl_b32 s47, s10, 8
	s_lshl_b32 s49, s1, 10
	v_ashrrev_i16_sdwa v2, v154, sext(v2) dst_sel:DWORD dst_unused:UNUSED_PAD src0_sel:DWORD src1_sel:BYTE_0
	s_add_i32 s5, s5, s6
	s_add_i32 s7, s8, s7
	s_mul_i32 s8, s48, s46
	v_sub_u32_e32 v7, v8, v7
	v_bfe_i32 v18, v2, 0, 16
	s_add_u32 s8, s20, s8
	v_ashrrev_i16_sdwa v7, v154, sext(v7) dst_sel:DWORD dst_unused:UNUSED_PAD src0_sel:DWORD src1_sel:BYTE_0
	v_add_u32_e32 v2, v17, v18
	v_mul_lo_u32 v3, v6, s10
	s_addc_u32 s9, s21, s7
	s_add_i32 s50, s49, 0
	v_bfe_i32 v15, v7, 0, 16
	v_add_lshl_u32 v136, v3, v2, 1
	s_add_i32 m0, s50, 0x10000
	v_add_u32_e32 v7, v14, v15
	v_mul_lo_u32 v8, v11, s10
	global_load_lds_dwordx4 v136, s[8:9]
	s_add_i32 m0, s50, 0x12000
	v_add_lshl_u32 v132, v8, v7, 1
	s_add_u32 s26, s8, s47
	global_load_lds_dwordx4 v132, s[8:9]
	s_addc_u32 s27, s9, 0
	s_add_i32 m0, s50, 0x14000
	s_mul_i32 s6, s24, s3
	global_load_lds_dwordx4 v136, s[26:27]
	s_add_i32 m0, s50, 0x16000
	s_add_u32 s6, s18, s6
	s_addc_u32 s7, s19, s5
	s_add_i32 s51, s50, 0x2000
	v_add_lshl_u32 v134, v2, v19, 1
	global_load_lds_dwordx4 v132, s[26:27]
	s_mov_b32 m0, s50
	s_add_u32 s28, s6, s14
	v_add_lshl_u32 v130, v7, v16, 1
	global_load_lds_dwordx4 v134, s[6:7]
	s_mov_b32 m0, s51
	s_addc_u32 s29, s7, 0
	s_add_i32 s52, s50, 0x4000
	global_load_lds_dwordx4 v130, s[6:7]
	s_mov_b32 m0, s52
	s_add_i32 s53, s50, 0x6000
	global_load_lds_dwordx4 v134, s[28:29]
	s_mov_b32 m0, s53
	v_mov_b32_e32 v137, v1
	global_load_lds_dwordx4 v130, s[28:29]
	v_mov_b32_e32 v133, v1
	v_mov_b32_e32 v135, v1
	v_mov_b32_e32 v131, v1
	s_cmp_eq_u32 s0, 1
	v_lshl_add_u64 v[10:11], s[8:9], 0, v[136:137]
	v_lshl_add_u64 v[6:7], s[8:9], 0, v[132:133]
	v_lshl_add_u64 v[4:5], s[26:27], 0, v[136:137]
	v_lshl_add_u64 v[2:3], s[26:27], 0, v[132:133]
	v_lshl_add_u64 v[8:9], s[6:7], 0, v[134:135]
	s_cselect_b64 s[26:27], -1, 0
	s_cmp_lg_u32 s0, 1
	v_lshl_add_u64 v[12:13], s[6:7], 0, v[130:131]
	s_cbranch_scc1 .LBB0_201
	s_barrier
.LBB0_201:
	s_cmp_eq_u32 s0, 1
	s_cbranch_scc0 .Lg1_noprio
	s_setprio 1
.Lg1_noprio:
	s_add_i32 m0, s50, 0x18000
	v_lshl_add_u64 v[10:11], v[10:11], 0, s[16:17]
	s_waitcnt vmcnt(2)
	s_barrier
	global_load_lds_dwordx4 v[10:11], off
	v_lshl_add_u64 v[6:7], v[6:7], 0, s[16:17]
	s_add_i32 m0, s50, 0x1a000
	s_add_i32 s54, s50, 0x8000
	global_load_lds_dwordx4 v[6:7], off
	v_lshl_add_u64 v[6:7], v[8:9], 0, s[16:17]
	s_mov_b32 m0, s54
	s_add_i32 s55, s50, 0xa000
	global_load_lds_dwordx4 v[6:7], off
	v_lshl_add_u64 v[6:7], v[12:13], 0, s[16:17]
	s_mov_b32 m0, s55
	v_lshl_add_u64 v[4:5], v[4:5], 0, s[16:17]
	global_load_lds_dwordx4 v[6:7], off
	s_add_i32 m0, s50, 0x1c000
	v_lshl_add_u64 v[2:3], v[2:3], 0, s[16:17]
	global_load_lds_dwordx4 v[4:5], off
	s_add_i32 m0, s50, 0x1e000
	s_and_b32 s1, s1, 3
	global_load_lds_dwordx4 v[2:3], off
	v_bfe_u32 v2, v0, 4, 2
	v_and_b32_e32 v3, 15, v0
	v_lshlrev_b32_e32 v4, 4, v2
	v_lshlrev_b32_e32 v0, 2, v0
	s_lshr_b32 s56, s10, 6
	v_lshl_or_b32 v155, s0, 6, v3
	v_lshl_or_b32 v3, v3, 6, v4
	s_lshl_b32 s0, s0, 13
	v_and_b32_e32 v0, 32, v0
	v_bitop3_b32 v4, v3, s0, v0 bitop3:0xde
	s_lshl_b32 s5, s1, 5
	s_lshl_b32 s0, s1, 12
	s_add_i32 s57, s56, -2
	s_cmpk_lt_u32 s4, 0x100
	s_cselect_b64 s[28:29], -1, 0
	s_cmp_eq_u32 s1, 2
	v_bitop3_b32 v156, v3, s0, v0 bitop3:0xde
	s_cselect_b64 s[0:1], -1, 0
	s_lshl_b32 s63, s34, 3
	v_cvt_f32_u32_e32 v0, s63
	v_cmp_eq_u32_e64 s[10:11], 0, v2
	s_and_b64 s[30:31], s[10:11], s[0:1]
	s_sub_i32 s0, 0, s63
	v_rcp_iflag_f32_e32 v0, v0
	s_waitcnt vmcnt(6)
	s_mov_b32 s64, 0
	v_lshl_or_b32 v138, v2, 3, s5
	v_mul_f32_e32 v0, 0x4f7ffffe, v0
	v_cvt_u32_f32_e32 v0, v0
	s_mov_b32 s23, s15
	s_lshl_b32 s65, s34, 4
	v_lshl_or_b32 v157, v2, 2, s5
	v_readfirstlane_b32 s1, v0
	v_add_u32_e32 v0, v19, v17
	v_add_lshl_u32 v0, v0, v18, 1
	s_mul_i32 s0, s0, s1
	v_lshl_add_u64 v[140:141], s[14:15], 0, v[0:1]
	v_add_u32_e32 v0, v16, v14
	s_mul_hi_u32 s0, s1, s0
	v_add_lshl_u32 v0, v0, v15, 1
	s_add_i32 s66, s1, s0
	v_lshl_add_u64 v[142:143], s[14:15], 0, v[0:1]
	v_add_u32_e32 v158, 0, v4
	s_barrier
	s_branch .LBB0_204

.LBB0_211:
	s_add_i32 s38, s8, 2
	s_add_u32 s39, s6, 0x80
	s_addc_u32 s9, s7, 0
	s_add_i32 s69, 0, 0x10000
	s_cmp_eq_u32 s57, s8
	s_cselect_b32 s9, s1, s9
	s_cselect_b32 s8, s0, s39
	v_add_u32_e32 v0, s69, v156
	s_cselect_b32 s59, s35, s37
	s_cselect_b32 s58, s34, s36
	s_add_i32 s39, 0, 0x14000
	ds_read_b128 v[144:147], v0
	ds_read_b128 v[148:151], v0 offset:1024
	ds_read_b128 v[160:163], v0 offset:2048
	ds_read_b128 v[164:167], v0 offset:3072
	v_add_u32_e32 v0, s39, v156
	ds_read_b128 v[168:171], v0
	ds_read_b128 v[172:175], v0 offset:1024
	ds_read_b128 v[176:179], v0 offset:2048
	ds_read_b128 v[180:183], v0 offset:3072
	v_lshl_add_u64 v[218:219], s[6:7], 0, v[140:141]
	s_add_i32 m0, s50, 0xc000
	ds_read_b128 v[184:187], v158
	ds_read_b128 v[188:191], v158 offset:1024
	ds_read_b128 v[192:195], v158 offset:2048
	ds_read_b128 v[196:199], v158 offset:3072
	ds_read_b128 v[202:205], v158 offset:4096
	ds_read_b128 v[206:209], v158 offset:5120
	ds_read_b128 v[210:213], v158 offset:6144
	ds_read_b128 v[214:217], v158 offset:7168
	global_load_lds_dwordx4 v[218:219], off
	v_lshl_add_u64 v[218:219], s[6:7], 0, v[142:143]
	s_add_i32 m0, s50, 0xe000
	s_nop 0
	global_load_lds_dwordx4 v[218:219], off
	s_waitcnt vmcnt(8)
	s_waitcnt lgkmcnt(0)
	s_barrier
	s_waitcnt lgkmcnt(0)
	v_mfma_f32_16x16x32_bf16 v[126:129], v[144:147], v[184:187], v[126:129]
	v_mfma_f32_16x16x32_bf16 v[122:125], v[160:163], v[184:187], v[122:125]
	v_mfma_f32_16x16x32_bf16 v[110:113], v[144:147], v[192:195], v[110:113]
	v_mfma_f32_16x16x32_bf16 v[106:109], v[160:163], v[192:195], v[106:109]
	v_mfma_f32_16x16x32_bf16 v[94:97], v[144:147], v[202:205], v[94:97]
	v_mfma_f32_16x16x32_bf16 v[90:93], v[160:163], v[202:205], v[90:93]
	v_mfma_f32_16x16x32_bf16 v[78:81], v[144:147], v[210:213], v[78:81]
	v_mfma_f32_16x16x32_bf16 v[74:77], v[160:163], v[210:213], v[74:77]
	v_mfma_f32_16x16x32_bf16 v[126:129], v[148:151], v[188:191], v[126:129]
	v_mfma_f32_16x16x32_bf16 v[122:125], v[164:167], v[188:191], v[122:125]
	v_mfma_f32_16x16x32_bf16 v[110:113], v[148:151], v[196:199], v[110:113]
	v_mfma_f32_16x16x32_bf16 v[106:109], v[164:167], v[196:199], v[106:109]
	v_mfma_f32_16x16x32_bf16 v[94:97], v[148:151], v[206:209], v[94:97]
	v_mfma_f32_16x16x32_bf16 v[90:93], v[164:167], v[206:209], v[90:93]
	v_mfma_f32_16x16x32_bf16 v[78:81], v[148:151], v[214:217], v[78:81]
	v_mfma_f32_16x16x32_bf16 v[74:77], v[164:167], v[214:217], v[74:77]
	v_mfma_f32_16x16x32_bf16 v[118:121], v[168:171], v[184:187], v[118:121]
	v_mfma_f32_16x16x32_bf16 v[114:117], v[176:179], v[184:187], v[114:117]
	v_mfma_f32_16x16x32_bf16 v[102:105], v[168:171], v[192:195], v[102:105]
	v_mfma_f32_16x16x32_bf16 v[98:101], v[176:179], v[192:195], v[98:101]
	v_mfma_f32_16x16x32_bf16 v[86:89], v[168:171], v[202:205], v[86:89]
	v_mfma_f32_16x16x32_bf16 v[82:85], v[176:179], v[202:205], v[82:85]
	v_mfma_f32_16x16x32_bf16 v[70:73], v[168:171], v[210:213], v[70:73]
	v_mfma_f32_16x16x32_bf16 v[66:69], v[176:179], v[210:213], v[66:69]
	v_mfma_f32_16x16x32_bf16 v[118:121], v[172:175], v[188:191], v[118:121]
	v_mfma_f32_16x16x32_bf16 v[114:117], v[180:183], v[188:191], v[114:117]
	v_mfma_f32_16x16x32_bf16 v[102:105], v[172:175], v[196:199], v[102:105]
	v_mfma_f32_16x16x32_bf16 v[98:101], v[180:183], v[196:199], v[98:101]
	v_mfma_f32_16x16x32_bf16 v[86:89], v[172:175], v[206:209], v[86:89]
	v_mfma_f32_16x16x32_bf16 v[82:85], v[180:183], v[206:209], v[82:85]
	v_mfma_f32_16x16x32_bf16 v[70:73], v[172:175], v[214:217], v[70:73]
	v_mfma_f32_16x16x32_bf16 v[66:69], v[180:183], v[214:217], v[66:69]
	s_barrier
	s_add_i32 s69, s69, s49
	v_lshl_add_u64 v[218:219], s[58:59], 0, v[136:137]
	s_mov_b32 m0, s69
	ds_read_b128 v[184:187], v158 offset:16384
	ds_read_b128 v[188:191], v158 offset:17408
	ds_read_b128 v[192:195], v158 offset:18432
	ds_read_b128 v[196:199], v158 offset:19456
	ds_read_b128 v[202:205], v158 offset:20480
	ds_read_b128 v[206:209], v158 offset:21504
	ds_read_b128 v[210:213], v158 offset:22528
	ds_read_b128 v[214:217], v158 offset:23552
	global_load_lds_dwordx4 v[218:219], off
	s_add_i32 m0, s69, 0x2000
	v_lshl_add_u64 v[220:221], s[58:59], 0, v[132:133]
	s_add_u32 s58, s58, s47
	s_addc_u32 s59, s59, 0
	s_add_i32 s39, s39, s49
	global_load_lds_dwordx4 v[220:221], off
	v_lshl_add_u64 v[222:223], s[58:59], 0, v[136:137]
	s_mov_b32 m0, s39
	v_lshl_add_u64 v[224:225], s[58:59], 0, v[132:133]
	global_load_lds_dwordx4 v[222:223], off
	s_add_i32 m0, s39, 0x2000
	v_lshl_add_u64 v[226:227], s[8:9], 0, v[134:135]
	global_load_lds_dwordx4 v[224:225], off
	s_mov_b32 m0, s50
	v_lshl_add_u64 v[228:229], s[8:9], 0, v[130:131]
	global_load_lds_dwordx4 v[226:227], off
	s_mov_b32 m0, s51
	s_nop 0
	global_load_lds_dwordx4 v[228:229], off
	s_waitcnt vmcnt(8)
	s_waitcnt lgkmcnt(0)
	s_barrier
	s_waitcnt lgkmcnt(0)
	v_mfma_f32_16x16x32_bf16 v[62:65], v[144:147], v[184:187], v[62:65]
	v_mfma_f32_16x16x32_bf16 v[58:61], v[160:163], v[184:187], v[58:61]
	v_mfma_f32_16x16x32_bf16 v[46:49], v[144:147], v[192:195], v[46:49]
	v_mfma_f32_16x16x32_bf16 v[42:45], v[160:163], v[192:195], v[42:45]
	v_mfma_f32_16x16x32_bf16 v[30:33], v[144:147], v[202:205], v[30:33]
	v_mfma_f32_16x16x32_bf16 v[26:29], v[160:163], v[202:205], v[26:29]
	v_mfma_f32_16x16x32_bf16 v[14:17], v[144:147], v[210:213], v[14:17]
	v_mfma_f32_16x16x32_bf16 v[10:13], v[160:163], v[210:213], v[10:13]
	v_mfma_f32_16x16x32_bf16 v[62:65], v[148:151], v[188:191], v[62:65]
	v_mfma_f32_16x16x32_bf16 v[58:61], v[164:167], v[188:191], v[58:61]
	v_mfma_f32_16x16x32_bf16 v[46:49], v[148:151], v[196:199], v[46:49]
	v_mfma_f32_16x16x32_bf16 v[42:45], v[164:167], v[196:199], v[42:45]
	v_mfma_f32_16x16x32_bf16 v[30:33], v[148:151], v[206:209], v[30:33]
	v_mfma_f32_16x16x32_bf16 v[26:29], v[164:167], v[206:209], v[26:29]
	v_mfma_f32_16x16x32_bf16 v[14:17], v[148:151], v[214:217], v[14:17]
	v_mfma_f32_16x16x32_bf16 v[10:13], v[164:167], v[214:217], v[10:13]
	v_mfma_f32_16x16x32_bf16 v[54:57], v[168:171], v[184:187], v[54:57]
	v_mfma_f32_16x16x32_bf16 v[50:53], v[176:179], v[184:187], v[50:53]
	v_mfma_f32_16x16x32_bf16 v[38:41], v[168:171], v[192:195], v[38:41]
	v_mfma_f32_16x16x32_bf16 v[34:37], v[176:179], v[192:195], v[34:37]
	v_mfma_f32_16x16x32_bf16 v[22:25], v[168:171], v[202:205], v[22:25]
	v_mfma_f32_16x16x32_bf16 v[18:21], v[176:179], v[202:205], v[18:21]
	v_mfma_f32_16x16x32_bf16 v[6:9], v[168:171], v[210:213], v[6:9]
	v_mfma_f32_16x16x32_bf16 v[2:5], v[176:179], v[210:213], v[2:5]
	v_mfma_f32_16x16x32_bf16 v[54:57], v[172:175], v[188:191], v[54:57]
	v_mfma_f32_16x16x32_bf16 v[50:53], v[180:183], v[188:191], v[50:53]
	v_mfma_f32_16x16x32_bf16 v[38:41], v[172:175], v[196:199], v[38:41]
	v_mfma_f32_16x16x32_bf16 v[34:37], v[180:183], v[196:199], v[34:37]
	v_mfma_f32_16x16x32_bf16 v[22:25], v[172:175], v[206:209], v[22:25]
	v_mfma_f32_16x16x32_bf16 v[18:21], v[180:183], v[206:209], v[18:21]
	v_mfma_f32_16x16x32_bf16 v[6:9], v[172:175], v[214:217], v[6:9]
	v_mfma_f32_16x16x32_bf16 v[2:5], v[180:183], v[214:217], v[2:5]
	s_barrier
	s_add_i32 s39, 0, 0x18000
	v_add_u32_e32 v0, s39, v156
	s_add_i32 s58, 0, 0x1c000
	ds_read_b128 v[144:147], v0
	ds_read_b128 v[148:151], v0 offset:1024
	ds_read_b128 v[160:163], v0 offset:2048
	ds_read_b128 v[164:167], v0 offset:3072
	v_add_u32_e32 v0, s58, v156
	ds_read_b128 v[168:171], v0
	ds_read_b128 v[172:175], v0 offset:1024
	ds_read_b128 v[176:179], v0 offset:2048
	ds_read_b128 v[180:183], v0 offset:3072
	s_add_u32 s8, s8, s14
	s_addc_u32 s9, s9, 0
	s_mov_b32 m0, s52
	v_lshl_add_u64 v[230:231], s[8:9], 0, v[134:135]
	ds_read_b128 v[184:187], v158 offset:32768
	ds_read_b128 v[188:191], v158 offset:33792
	ds_read_b128 v[192:195], v158 offset:34816
	ds_read_b128 v[196:199], v158 offset:35840
	ds_read_b128 v[202:205], v158 offset:36864
	ds_read_b128 v[206:209], v158 offset:37888
	ds_read_b128 v[210:213], v158 offset:38912
	ds_read_b128 v[214:217], v158 offset:39936
	global_load_lds_dwordx4 v[230:231], off
	v_lshl_add_u64 v[230:231], s[8:9], 0, v[130:131]
	s_mov_b32 m0, s53
	s_nop 0
	global_load_lds_dwordx4 v[230:231], off
	s_waitcnt vmcnt(8)
	s_waitcnt lgkmcnt(0)
	s_barrier
	s_waitcnt lgkmcnt(0)
	v_mfma_f32_16x16x32_bf16 v[126:129], v[144:147], v[184:187], v[126:129]
	v_mfma_f32_16x16x32_bf16 v[122:125], v[160:163], v[184:187], v[122:125]
	v_mfma_f32_16x16x32_bf16 v[110:113], v[144:147], v[192:195], v[110:113]
	v_mfma_f32_16x16x32_bf16 v[106:109], v[160:163], v[192:195], v[106:109]
	v_mfma_f32_16x16x32_bf16 v[94:97], v[144:147], v[202:205], v[94:97]
	v_mfma_f32_16x16x32_bf16 v[90:93], v[160:163], v[202:205], v[90:93]
	v_mfma_f32_16x16x32_bf16 v[78:81], v[144:147], v[210:213], v[78:81]
	v_mfma_f32_16x16x32_bf16 v[74:77], v[160:163], v[210:213], v[74:77]
	v_mfma_f32_16x16x32_bf16 v[126:129], v[148:151], v[188:191], v[126:129]
	v_mfma_f32_16x16x32_bf16 v[122:125], v[164:167], v[188:191], v[122:125]
	v_mfma_f32_16x16x32_bf16 v[110:113], v[148:151], v[196:199], v[110:113]
	v_mfma_f32_16x16x32_bf16 v[106:109], v[164:167], v[196:199], v[106:109]
	v_mfma_f32_16x16x32_bf16 v[94:97], v[148:151], v[206:209], v[94:97]
	v_mfma_f32_16x16x32_bf16 v[90:93], v[164:167], v[206:209], v[90:93]
	v_mfma_f32_16x16x32_bf16 v[78:81], v[148:151], v[214:217], v[78:81]
	v_mfma_f32_16x16x32_bf16 v[74:77], v[164:167], v[214:217], v[74:77]
	v_mfma_f32_16x16x32_bf16 v[118:121], v[168:171], v[184:187], v[118:121]
	v_mfma_f32_16x16x32_bf16 v[114:117], v[176:179], v[184:187], v[114:117]
	v_mfma_f32_16x16x32_bf16 v[102:105], v[168:171], v[192:195], v[102:105]
	v_mfma_f32_16x16x32_bf16 v[98:101], v[176:179], v[192:195], v[98:101]
	v_mfma_f32_16x16x32_bf16 v[86:89], v[168:171], v[202:205], v[86:89]
	v_mfma_f32_16x16x32_bf16 v[82:85], v[176:179], v[202:205], v[82:85]
	v_mfma_f32_16x16x32_bf16 v[70:73], v[168:171], v[210:213], v[70:73]
	v_mfma_f32_16x16x32_bf16 v[66:69], v[176:179], v[210:213], v[66:69]
	v_mfma_f32_16x16x32_bf16 v[118:121], v[172:175], v[188:191], v[118:121]
	v_mfma_f32_16x16x32_bf16 v[114:117], v[180:183], v[188:191], v[114:117]
	v_mfma_f32_16x16x32_bf16 v[102:105], v[172:175], v[196:199], v[102:105]
	v_mfma_f32_16x16x32_bf16 v[98:101], v[180:183], v[196:199], v[98:101]
	v_mfma_f32_16x16x32_bf16 v[86:89], v[172:175], v[206:209], v[86:89]
	v_mfma_f32_16x16x32_bf16 v[82:85], v[180:183], v[206:209], v[82:85]
	v_mfma_f32_16x16x32_bf16 v[70:73], v[172:175], v[214:217], v[70:73]
	v_mfma_f32_16x16x32_bf16 v[66:69], v[180:183], v[214:217], v[66:69]
	s_barrier
	s_add_i32 s8, s39, s49
	v_lshl_add_u64 v[218:219], v[218:219], 0, s[16:17]
	s_mov_b32 m0, s8
	ds_read_b128 v[184:187], v158 offset:49152
	ds_read_b128 v[188:191], v158 offset:50176
	ds_read_b128 v[192:195], v158 offset:51200
	ds_read_b128 v[196:199], v158 offset:52224
	ds_read_b128 v[202:205], v158 offset:53248
	ds_read_b128 v[206:209], v158 offset:54272
	ds_read_b128 v[210:213], v158 offset:55296
	ds_read_b128 v[214:217], v158 offset:56320
	global_load_lds_dwordx4 v[218:219], off
	v_lshl_add_u64 v[218:219], v[220:221], 0, s[16:17]
	s_add_i32 m0, s8, 0x2000
	s_add_i32 s8, s58, s49
	global_load_lds_dwordx4 v[218:219], off
	v_lshl_add_u64 v[218:219], v[222:223], 0, s[16:17]
	s_mov_b32 m0, s8
	s_nop 0
	global_load_lds_dwordx4 v[218:219], off
	v_lshl_add_u64 v[218:219], v[224:225], 0, s[16:17]
	s_add_i32 m0, s8, 0x2000
	s_nop 0
	global_load_lds_dwordx4 v[218:219], off
	v_lshl_add_u64 v[218:219], v[226:227], 0, s[16:17]
	s_mov_b32 m0, s54
	s_nop 0
	global_load_lds_dwordx4 v[218:219], off
	v_lshl_add_u64 v[218:219], v[228:229], 0, s[16:17]
	s_mov_b32 m0, s55
	s_nop 0
	global_load_lds_dwordx4 v[218:219], off
	s_waitcnt vmcnt(8)
	s_waitcnt lgkmcnt(0)
	s_barrier
	s_waitcnt lgkmcnt(0)
	v_mfma_f32_16x16x32_bf16 v[62:65], v[144:147], v[184:187], v[62:65]
	v_mfma_f32_16x16x32_bf16 v[58:61], v[160:163], v[184:187], v[58:61]
	v_mfma_f32_16x16x32_bf16 v[46:49], v[144:147], v[192:195], v[46:49]
	v_mfma_f32_16x16x32_bf16 v[42:45], v[160:163], v[192:195], v[42:45]
	v_mfma_f32_16x16x32_bf16 v[30:33], v[144:147], v[202:205], v[30:33]
	v_mfma_f32_16x16x32_bf16 v[26:29], v[160:163], v[202:205], v[26:29]
	v_mfma_f32_16x16x32_bf16 v[14:17], v[144:147], v[210:213], v[14:17]
	v_mfma_f32_16x16x32_bf16 v[10:13], v[160:163], v[210:213], v[10:13]
	v_mfma_f32_16x16x32_bf16 v[62:65], v[148:151], v[188:191], v[62:65]
	v_mfma_f32_16x16x32_bf16 v[58:61], v[164:167], v[188:191], v[58:61]
	v_mfma_f32_16x16x32_bf16 v[46:49], v[148:151], v[196:199], v[46:49]
	v_mfma_f32_16x16x32_bf16 v[42:45], v[164:167], v[196:199], v[42:45]
	v_mfma_f32_16x16x32_bf16 v[30:33], v[148:151], v[206:209], v[30:33]
	v_mfma_f32_16x16x32_bf16 v[26:29], v[164:167], v[206:209], v[26:29]
	v_mfma_f32_16x16x32_bf16 v[14:17], v[148:151], v[214:217], v[14:17]
	v_mfma_f32_16x16x32_bf16 v[10:13], v[164:167], v[214:217], v[10:13]
	v_mfma_f32_16x16x32_bf16 v[54:57], v[168:171], v[184:187], v[54:57]
	v_mfma_f32_16x16x32_bf16 v[50:53], v[176:179], v[184:187], v[50:53]
	v_mfma_f32_16x16x32_bf16 v[38:41], v[168:171], v[192:195], v[38:41]
	v_mfma_f32_16x16x32_bf16 v[34:37], v[176:179], v[192:195], v[34:37]
	v_mfma_f32_16x16x32_bf16 v[22:25], v[168:171], v[202:205], v[22:25]
	v_mfma_f32_16x16x32_bf16 v[18:21], v[176:179], v[202:205], v[18:21]
	v_mfma_f32_16x16x32_bf16 v[6:9], v[168:171], v[210:213], v[6:9]
	v_mfma_f32_16x16x32_bf16 v[2:5], v[176:179], v[210:213], v[2:5]
	v_mfma_f32_16x16x32_bf16 v[54:57], v[172:175], v[188:191], v[54:57]
	v_mfma_f32_16x16x32_bf16 v[50:53], v[180:183], v[188:191], v[50:53]
	v_mfma_f32_16x16x32_bf16 v[38:41], v[172:175], v[196:199], v[38:41]
	v_mfma_f32_16x16x32_bf16 v[34:37], v[180:183], v[196:199], v[34:37]
	v_mfma_f32_16x16x32_bf16 v[22:25], v[172:175], v[206:209], v[22:25]
	v_mfma_f32_16x16x32_bf16 v[18:21], v[180:183], v[206:209], v[18:21]
	v_mfma_f32_16x16x32_bf16 v[6:9], v[172:175], v[214:217], v[6:9]
	v_mfma_f32_16x16x32_bf16 v[2:5], v[180:183], v[214:217], v[2:5]
	s_barrier
	s_add_u32 s6, s6, 0x100
	s_addc_u32 s7, s7, 0
	s_add_u32 s36, s36, 0x100
	s_addc_u32 s37, s37, 0
	s_cmp_ge_u32 s38, s56
	s_mov_b32 s8, s38
	s_cbranch_scc0 .LBB0_211
	s_and_b64 vcc, exec, s[28:29]
	s_cbranch_vccnz .LBB0_215
	s_lshl_b32 s8, s3, 8
	s_cmp_lt_i32 s45, 2
	s_mov_b64 s[6:7], -1
	s_cbranch_scc0 .LBB0_216

.LBB0_314:
	s_or_b64 exec, exec, s[6:7]
	s_and_b64 vcc, exec, s[4:5]
	s_mov_b64 s[4:5], -1
	s_cbranch_vccnz .LBB0_203
	s_branch .LBB0_308
.LBB0_315:
	s_setprio 0
	s_waitcnt vmcnt(0)
	s_barrier
.LBB0_316:
	v_cndmask_b32_e64 v0, 0, 1, s[12:13]
	v_cmp_ne_u32_e64 s[0:1], 1, v0
	s_andn2_b64 vcc, exec, s[12:13]
	s_nop 0
	v_writelane_b32 v255, s0, 44
	s_nop 1
	v_writelane_b32 v255, s1, 45
	s_cbranch_vccnz .LBB0_498
	s_cmp_lt_i32 s45, 2
	s_mov_b64 s[0:1], -1
	s_cbranch_scc1 .LBB0_410
	s_cmp_eq_u32 s45, 2
	s_cbranch_scc0 .LBB0_409
	v_mov_b32_e32 v0, v200
	v_readlane_b32 s1, v254, 47
	v_readfirstlane_b32 s0, v0
	s_ashr_i32 s0, s0, 6
	s_add_i32 s3, s0, s1
	s_cmpk_gt_i32 s3, 0xc2f
	s_cbranch_scc1 .LBB0_409
	v_bfe_u32 v10, v0, 4, 2
	s_waitcnt lgkmcnt(0)
	v_lshlrev_b32_e32 v2, 2, v0
	v_bfe_u32 v30, v0, 3, 3
	v_lshlrev_b32_e32 v0, 3, v0
	s_mul_i32 s1, s0, 0x4100
	v_and_b32_e32 v0, 56, v0
	s_add_i32 s1, s1, 0
	v_and_b32_e32 v12, 60, v2
	v_mul_u32_u24_e32 v4, 0x104, v0
	v_lshlrev_b32_e32 v5, 2, v30
	v_lshl_add_u32 v2, v12, 2, s1
	v_mul_u32_u24_e32 v3, 0x104, v10
	v_add3_u32 v31, s1, v4, v5
	v_readlane_b32 s1, v255, 42
	v_or_b32_e32 v13, 4, v10
	v_or_b32_e32 v16, 8, v10
	v_or_b32_e32 v17, 12, v10
	v_or_b32_e32 v18, 16, v10
	v_or_b32_e32 v19, 20, v10
	v_or_b32_e32 v20, 24, v10
	v_or_b32_e32 v21, 28, v10
	v_or_b32_e32 v22, 32, v10
	v_or_b32_e32 v23, 36, v10
	v_or_b32_e32 v24, 40, v10
	v_or_b32_e32 v25, 44, v10
	v_or_b32_e32 v26, 48, v10
	v_or_b32_e32 v27, 52, v10
	v_or_b32_e32 v28, 56, v10
	v_or_b32_e32 v29, 60, v10
	v_or_b32_e32 v32, 8, v30
	v_or_b32_e32 v33, 16, v30
	v_or_b32_e32 v34, 24, v30
	v_or_b32_e32 v35, 32, v30
	v_or_b32_e32 v36, 40, v30
	v_or_b32_e32 v37, 48, v30
	v_or_b32_e32 v38, 56, v30
	v_mov_b32_e32 v11, v1
	s_add_i32 s14, s1, s0
	v_lshlrev_b32_e32 v14, 1, v0
	v_add_u32_e32 v39, v2, v3
	s_branch .LBB0_322
